# MODE3 epilogue: conv weights loaded straight from global into registers at epilogue start (overlaps the LDS tile write), LDS staging round trip removed
# speedup vs baseline: 1.0072x; 1.0072x over previous
.LBB0_1146:
	v_mov_b32_e32 v130, v224
	v_readlane_b32 s80, v255, 38
	v_readlane_b32 s81, v255, 39
	s_lshl_b32 s22, s77, 7
	v_and_b32_e32 v208, 31, v224
	s_lshl_b32 s82, s77, 9
	v_lshlrev_b32_e32 v208, 4, v208
	v_lshlrev_b32_e32 v129, 2, v130
	v_add_u32_e32 v208, s82, v208
	v_mov_b32_e32 v128, s22
	global_load_dwordx4 v[184:187], v208, s[80:81]
	s_add_u32 s82, s80, 0xb000
	s_addc_u32 s83, s81, 0
	global_load_dwordx4 v[188:191], v208, s[82:83]
	s_add_u32 s82, s80, 0x16000
	s_addc_u32 s83, s81, 0
	global_load_dwordx4 v[192:195], v208, s[82:83]
	s_add_u32 s82, s80, 0x5800
	s_addc_u32 s83, s81, 0
	global_load_dwordx4 v[196:199], v208, s[82:83]
	s_add_u32 s82, s80, 0x10800
	s_addc_u32 s83, s81, 0
	global_load_dwordx4 v[200:203], v208, s[82:83]
	s_add_u32 s82, s80, 0x1b800
	s_addc_u32 s83, s81, 0
	global_load_dwordx4 v[204:207], v208, s[82:83]
	s_and_b64 vcc, exec, s[6:7]
	s_waitcnt lgkmcnt(0)
	v_add_u32_e32 v162, 0x400, v225
	v_add_u32_e32 v163, 0x800, v225
	v_add_u32_e32 v164, 0xc00, v225
	v_add_u32_e32 v157, 0x4000, v225
	v_add_u32_e32 v158, 0x4400, v225
	v_add_u32_e32 v159, 0x4800, v225
	v_add_u32_e32 v160, 0x4c00, v225
	v_add_u32_e32 v161, 0x8000, v225
	v_add_u32_e32 v152, 0x8400, v225
	v_add_u32_e32 v153, 0x8800, v225
	v_add_u32_e32 v154, 0x8c00, v225
	v_add_u32_e32 v155, 0x9000, v225
	v_add_u32_e32 v156, 0xc000, v225
	v_add_u32_e32 v148, 0xc400, v225
	v_add_u32_e32 v149, 0xc800, v225
	v_add_u32_e32 v150, 0xcc00, v225
	v_add_u32_e32 v151, 0xd000, v225
	s_cbranch_vccnz .LBB0_1152
	ds_write2_b32 v225, v88, v92 offset1:16
	ds_write2_b32 v162, v89, v93 offset0:4 offset1:20
	ds_write2_b32 v163, v90, v94 offset0:8 offset1:24
	ds_write2_b32 v164, v91, v95 offset0:12 offset1:28
	ds_write2_b32 v225, v120, v124 offset0:128 offset1:144
	ds_write2_b32 v162, v121, v125 offset0:132 offset1:148
	ds_write2_b32 v163, v122, v126 offset0:136 offset1:152
	ds_write2_b32 v164, v123, v127 offset0:140 offset1:156
	ds_write2_b32 v157, v80, v84 offset0:64 offset1:80
	ds_write2_b32 v158, v81, v85 offset0:68 offset1:84
	ds_write2_b32 v159, v82, v86 offset0:72 offset1:88
	ds_write2_b32 v160, v83, v87 offset0:76 offset1:92
	ds_write2_b32 v157, v112, v116 offset0:192 offset1:208
	ds_write2_b32 v158, v113, v117 offset0:196 offset1:212
	ds_write2_b32 v159, v114, v118 offset0:200 offset1:216
	ds_write2_b32 v160, v115, v119 offset0:204 offset1:220
	ds_write2_b32 v161, v72, v76 offset0:128 offset1:144
	ds_write2_b32 v152, v73, v77 offset0:132 offset1:148
	ds_write2_b32 v153, v74, v78 offset0:136 offset1:152
	ds_write2_b32 v154, v75, v79 offset0:140 offset1:156
	ds_write2_b32 v152, v104, v108 offset1:16
	ds_write2_b32 v153, v105, v109 offset0:4 offset1:20
	ds_write2_b32 v154, v106, v110 offset0:8 offset1:24
	ds_write2_b32 v155, v107, v111 offset0:12 offset1:28
	ds_write2_b32 v156, v64, v68 offset0:192 offset1:208
	ds_write2_b32 v148, v65, v69 offset0:196 offset1:212
	ds_write2_b32 v149, v66, v70 offset0:200 offset1:216
	ds_write2_b32 v150, v67, v71 offset0:204 offset1:220
	ds_write2_b32 v148, v96, v100 offset0:64 offset1:80
	ds_write2_b32 v149, v97, v101 offset0:68 offset1:84
	ds_write2_b32 v150, v98, v102 offset0:72 offset1:88
	ds_write2_b32 v151, v99, v103 offset0:76 offset1:92
